# P8 epilogue: dropped three redundant s_nop per group (trans-result wait state already met by instruction order)
# speedup vs baseline: 1.0204x; 1.0022x over previous
.Lp8_loop_exit:
	v_lshl_or_b32 v176, s46, 7, v239
	s_cmp_gt_i32 s20, 63
	v_ashrrev_i32_e32 v177, 31, v176
	s_mov_b64 s[46:47], -1
	s_cbranch_scc1 .LBB0_1141
	v_add_u32_e32 v251, s86, v250
	ds_read_b128 v[130:133], v251
	ds_read_b128 v[146:149], v251 offset:512
	ds_read_b128 v[134:137], v251 offset:1024
	ds_read_b128 v[150:153], v251 offset:1536
	ds_read_b128 v[138:141], v251 offset:2048
	ds_read_b128 v[154:157], v251 offset:2560
	ds_read_b128 v[142:145], v251 offset:3072
	ds_read_b128 v[158:161], v251 offset:3584
	ds_read_b128 v[178:181], v251 offset:64
	ds_read_b128 v[194:197], v251 offset:576
	ds_read_b128 v[182:185], v251 offset:1088
	ds_read_b128 v[198:201], v251 offset:1600
	ds_read_b128 v[186:189], v251 offset:2112
	ds_read_b128 v[202:205], v251 offset:2624
	ds_read_b128 v[190:193], v251 offset:3136
	ds_read_b128 v[206:209], v251 offset:3648
	s_lshl_b32 s39, s20, 2
	s_add_i32 s39, s39, s55
	s_mov_b32 s96, 0x2c000
	s_mov_b32 s97, 0
	s_mov_b32 s48, 0xbfb8aa3b
	v_mov_b32_e32 v211, 0
	v_mov_b32_e32 v213, 0
	v_mov_b32_e32 v215, 0
	v_mov_b32_e32 v217, 0
	v_mov_b32_e32 v219, 0
	v_lshlrev_b32_e32 v243, 2, v176
	v_lshlrev_b32_e32 v244, 1, v176
	v_mul_u32_u24_e32 v210, 0x2c00, v1
	v_add_u32_e32 v210, v210, v244
	v_mul_u32_u24_e32 v212, 0xb000, v1
	v_add_u32_e32 v212, v212, v243
	v_add_u32_e32 v214, 0x5800, v212
	v_mul_i32_i24_e32 v216, 0xb000, v237
	v_add_u32_e32 v216, v216, v243
	v_add_u32_e32 v218, 0x5800, v216
	s_waitcnt lgkmcnt(0)
	s_add_i32 s84, s39, 0
	s_mul_i32 s85, s84, 0xb0000
	s_add_u32 s94, s22, s85
	s_addc_u32 s95, s23, 0
	v_lshl_add_u64 v[220:221], s[94:95], 0, v[210:211]
	s_mul_i32 s85, s84, 0x16000
	s_add_u32 s94, s24, s85
	s_addc_u32 s95, s25, 0
	v_lshl_add_u64 v[222:223], s[94:95], 0, v[212:213]
	v_lshl_add_u64 v[246:247], s[94:95], 0, v[214:215]
	s_and_saveexec_b64 s[46:47], s[4:5]
	global_store_dwordx4 v[222:223], v[126:129], off
	global_store_dwordx4 v[246:247], v[110:113], off
	s_or_b64 exec, exec, s[46:47]
	v_pk_fma_f32 v[224:225], v[126:127], v[138:139], v[142:143]
	v_pk_fma_f32 v[226:227], v[128:129], v[140:141], v[144:145]
	v_pk_fma_f32 v[228:229], v[110:111], v[154:155], v[158:159]
	v_pk_fma_f32 v[230:231], v[112:113], v[156:157], v[160:161]
	v_fmac_f32_dpp v224, v126, v134 row_shr:1 row_mask:0xf bank_mask:0xf bound_ctrl:1
	v_fmac_f32_dpp v225, v127, v135 row_shr:1 row_mask:0xf bank_mask:0xf bound_ctrl:1
	v_fmac_f32_dpp v226, v128, v136 row_shr:1 row_mask:0xf bank_mask:0xf bound_ctrl:1
	v_fmac_f32_dpp v227, v129, v137 row_shr:1 row_mask:0xf bank_mask:0xf bound_ctrl:1
	v_fmac_f32_dpp v228, v110, v150 row_shr:1 row_mask:0xf bank_mask:0xf bound_ctrl:1
	v_fmac_f32_dpp v229, v111, v151 row_shr:1 row_mask:0xf bank_mask:0xf bound_ctrl:1
	v_fmac_f32_dpp v230, v112, v152 row_shr:1 row_mask:0xf bank_mask:0xf bound_ctrl:1
	v_fmac_f32_dpp v231, v113, v153 row_shr:1 row_mask:0xf bank_mask:0xf bound_ctrl:1
	v_fmac_f32_dpp v224, v126, v130 row_shr:2 row_mask:0xf bank_mask:0xf bound_ctrl:1
	v_fmac_f32_dpp v225, v127, v131 row_shr:2 row_mask:0xf bank_mask:0xf bound_ctrl:1
	v_fmac_f32_dpp v226, v128, v132 row_shr:2 row_mask:0xf bank_mask:0xf bound_ctrl:1
	v_fmac_f32_dpp v227, v129, v133 row_shr:2 row_mask:0xf bank_mask:0xf bound_ctrl:1
	v_fmac_f32_dpp v228, v110, v146 row_shr:2 row_mask:0xf bank_mask:0xf bound_ctrl:1
	v_fmac_f32_dpp v229, v111, v147 row_shr:2 row_mask:0xf bank_mask:0xf bound_ctrl:1
	v_fmac_f32_dpp v230, v112, v148 row_shr:2 row_mask:0xf bank_mask:0xf bound_ctrl:1
	v_fmac_f32_dpp v231, v113, v149 row_shr:2 row_mask:0xf bank_mask:0xf bound_ctrl:1
	v_pk_mul_f32 v[232:233], v[224:225], s[48:49] op_sel_hi:[1,0]
	v_pk_mul_f32 v[234:235], v[226:227], s[48:49] op_sel_hi:[1,0]
	v_exp_f32_e32 v232, v232
	v_exp_f32_e32 v233, v233
	v_exp_f32_e32 v234, v234
	v_exp_f32_e32 v235, v235
	v_pk_add_f32 v[232:233], v[232:233], 1.0 op_sel_hi:[1,0]
	v_pk_add_f32 v[234:235], v[234:235], 1.0 op_sel_hi:[1,0]
	v_rcp_f32_e32 v232, v232
	v_rcp_f32_e32 v233, v233
	v_rcp_f32_e32 v234, v234
	v_rcp_f32_e32 v235, v235
	v_pk_mul_f32 v[224:225], v[224:225], v[232:233]
	v_pk_mul_f32 v[226:227], v[226:227], v[234:235]
	v_pk_mul_f32 v[224:225], v[224:225], v[228:229]
	v_pk_mul_f32 v[226:227], v[226:227], v[230:231]
	v_cvt_pk_bf16_f32 v168, v224, v225
	v_cvt_pk_bf16_f32 v169, v226, v227
	s_and_saveexec_b64 s[46:47], s[8:9]
	global_store_dwordx2 v[220:221], v[168:169], off
	s_or_b64 exec, exec, s[46:47]
	v_pk_fma_f32 v[224:225], v[118:119], v[138:139], v[142:143]
	v_pk_fma_f32 v[226:227], v[120:121], v[140:141], v[144:145]
	v_pk_fma_f32 v[228:229], v[94:95], v[154:155], v[158:159]
	v_pk_fma_f32 v[230:231], v[96:97], v[156:157], v[160:161]
	v_fmac_f32_dpp v224, v118, v134 row_shr:1 row_mask:0xf bank_mask:0xf bound_ctrl:1
	v_fmac_f32_dpp v225, v119, v135 row_shr:1 row_mask:0xf bank_mask:0xf bound_ctrl:1
	v_fmac_f32_dpp v226, v120, v136 row_shr:1 row_mask:0xf bank_mask:0xf bound_ctrl:1
	v_fmac_f32_dpp v227, v121, v137 row_shr:1 row_mask:0xf bank_mask:0xf bound_ctrl:1
	v_fmac_f32_dpp v228, v94, v150 row_shr:1 row_mask:0xf bank_mask:0xf bound_ctrl:1
	v_fmac_f32_dpp v229, v95, v151 row_shr:1 row_mask:0xf bank_mask:0xf bound_ctrl:1
	v_fmac_f32_dpp v230, v96, v152 row_shr:1 row_mask:0xf bank_mask:0xf bound_ctrl:1
	v_fmac_f32_dpp v231, v97, v153 row_shr:1 row_mask:0xf bank_mask:0xf bound_ctrl:1
	v_fmac_f32_dpp v224, v118, v130 row_shr:2 row_mask:0xf bank_mask:0xf bound_ctrl:1
	v_fmac_f32_dpp v225, v119, v131 row_shr:2 row_mask:0xf bank_mask:0xf bound_ctrl:1
	v_fmac_f32_dpp v226, v120, v132 row_shr:2 row_mask:0xf bank_mask:0xf bound_ctrl:1
	v_fmac_f32_dpp v227, v121, v133 row_shr:2 row_mask:0xf bank_mask:0xf bound_ctrl:1
	v_fmac_f32_dpp v228, v94, v146 row_shr:2 row_mask:0xf bank_mask:0xf bound_ctrl:1
	v_fmac_f32_dpp v229, v95, v147 row_shr:2 row_mask:0xf bank_mask:0xf bound_ctrl:1
	v_fmac_f32_dpp v230, v96, v148 row_shr:2 row_mask:0xf bank_mask:0xf bound_ctrl:1
	v_fmac_f32_dpp v231, v97, v149 row_shr:2 row_mask:0xf bank_mask:0xf bound_ctrl:1
	v_fmac_f32_dpp v224, v126, v134 row_shl:15 row_mask:0xf bank_mask:0xf bound_ctrl:1
	v_fmac_f32_dpp v225, v127, v135 row_shl:15 row_mask:0xf bank_mask:0xf bound_ctrl:1
	v_fmac_f32_dpp v226, v128, v136 row_shl:15 row_mask:0xf bank_mask:0xf bound_ctrl:1
	v_fmac_f32_dpp v227, v129, v137 row_shl:15 row_mask:0xf bank_mask:0xf bound_ctrl:1
	v_fmac_f32_dpp v228, v110, v150 row_shl:15 row_mask:0xf bank_mask:0xf bound_ctrl:1
	v_fmac_f32_dpp v229, v111, v151 row_shl:15 row_mask:0xf bank_mask:0xf bound_ctrl:1
	v_fmac_f32_dpp v230, v112, v152 row_shl:15 row_mask:0xf bank_mask:0xf bound_ctrl:1
	v_fmac_f32_dpp v231, v113, v153 row_shl:15 row_mask:0xf bank_mask:0xf bound_ctrl:1
	v_fmac_f32_dpp v224, v126, v130 row_shl:14 row_mask:0xf bank_mask:0xf bound_ctrl:1
	v_fmac_f32_dpp v225, v127, v131 row_shl:14 row_mask:0xf bank_mask:0xf bound_ctrl:1
	v_fmac_f32_dpp v226, v128, v132 row_shl:14 row_mask:0xf bank_mask:0xf bound_ctrl:1
	v_fmac_f32_dpp v227, v129, v133 row_shl:14 row_mask:0xf bank_mask:0xf bound_ctrl:1
	v_fmac_f32_dpp v228, v110, v146 row_shl:14 row_mask:0xf bank_mask:0xf bound_ctrl:1
	v_fmac_f32_dpp v229, v111, v147 row_shl:14 row_mask:0xf bank_mask:0xf bound_ctrl:1
	v_fmac_f32_dpp v230, v112, v148 row_shl:14 row_mask:0xf bank_mask:0xf bound_ctrl:1
	v_fmac_f32_dpp v231, v113, v149 row_shl:14 row_mask:0xf bank_mask:0xf bound_ctrl:1
	v_pk_mul_f32 v[232:233], v[224:225], s[48:49] op_sel_hi:[1,0]
	v_pk_mul_f32 v[234:235], v[226:227], s[48:49] op_sel_hi:[1,0]
	v_exp_f32_e32 v232, v232
	v_exp_f32_e32 v233, v233
	v_exp_f32_e32 v234, v234
	v_exp_f32_e32 v235, v235
	v_pk_add_f32 v[232:233], v[232:233], 1.0 op_sel_hi:[1,0]
	v_pk_add_f32 v[234:235], v[234:235], 1.0 op_sel_hi:[1,0]
	v_rcp_f32_e32 v232, v232
	v_rcp_f32_e32 v233, v233
	v_rcp_f32_e32 v234, v234
	v_rcp_f32_e32 v235, v235
	v_lshl_add_u64 v[220:221], v[220:221], 0, s[96:97]
	v_pk_mul_f32 v[224:225], v[224:225], v[232:233]
	v_pk_mul_f32 v[226:227], v[226:227], v[234:235]
	v_pk_mul_f32 v[224:225], v[224:225], v[228:229]
	v_pk_mul_f32 v[226:227], v[226:227], v[230:231]
	v_cvt_pk_bf16_f32 v168, v224, v225
	v_cvt_pk_bf16_f32 v169, v226, v227
	global_store_dwordx2 v[220:221], v[168:169], off
	v_pk_fma_f32 v[224:225], v[106:107], v[138:139], v[142:143]
	v_pk_fma_f32 v[226:227], v[108:109], v[140:141], v[144:145]
	v_pk_fma_f32 v[228:229], v[78:79], v[154:155], v[158:159]
	v_pk_fma_f32 v[230:231], v[80:81], v[156:157], v[160:161]
	v_fmac_f32_dpp v224, v106, v134 row_shr:1 row_mask:0xf bank_mask:0xf bound_ctrl:1
	v_fmac_f32_dpp v225, v107, v135 row_shr:1 row_mask:0xf bank_mask:0xf bound_ctrl:1
	v_fmac_f32_dpp v226, v108, v136 row_shr:1 row_mask:0xf bank_mask:0xf bound_ctrl:1
	v_fmac_f32_dpp v227, v109, v137 row_shr:1 row_mask:0xf bank_mask:0xf bound_ctrl:1
	v_fmac_f32_dpp v228, v78, v150 row_shr:1 row_mask:0xf bank_mask:0xf bound_ctrl:1
	v_fmac_f32_dpp v229, v79, v151 row_shr:1 row_mask:0xf bank_mask:0xf bound_ctrl:1
	v_fmac_f32_dpp v230, v80, v152 row_shr:1 row_mask:0xf bank_mask:0xf bound_ctrl:1
	v_fmac_f32_dpp v231, v81, v153 row_shr:1 row_mask:0xf bank_mask:0xf bound_ctrl:1
	v_fmac_f32_dpp v224, v106, v130 row_shr:2 row_mask:0xf bank_mask:0xf bound_ctrl:1
	v_fmac_f32_dpp v225, v107, v131 row_shr:2 row_mask:0xf bank_mask:0xf bound_ctrl:1
	v_fmac_f32_dpp v226, v108, v132 row_shr:2 row_mask:0xf bank_mask:0xf bound_ctrl:1
	v_fmac_f32_dpp v227, v109, v133 row_shr:2 row_mask:0xf bank_mask:0xf bound_ctrl:1
	v_fmac_f32_dpp v228, v78, v146 row_shr:2 row_mask:0xf bank_mask:0xf bound_ctrl:1
	v_fmac_f32_dpp v229, v79, v147 row_shr:2 row_mask:0xf bank_mask:0xf bound_ctrl:1
	v_fmac_f32_dpp v230, v80, v148 row_shr:2 row_mask:0xf bank_mask:0xf bound_ctrl:1
	v_fmac_f32_dpp v231, v81, v149 row_shr:2 row_mask:0xf bank_mask:0xf bound_ctrl:1
	v_fmac_f32_dpp v224, v118, v134 row_shl:15 row_mask:0xf bank_mask:0xf bound_ctrl:1
	v_fmac_f32_dpp v225, v119, v135 row_shl:15 row_mask:0xf bank_mask:0xf bound_ctrl:1
	v_fmac_f32_dpp v226, v120, v136 row_shl:15 row_mask:0xf bank_mask:0xf bound_ctrl:1
	v_fmac_f32_dpp v227, v121, v137 row_shl:15 row_mask:0xf bank_mask:0xf bound_ctrl:1
	v_fmac_f32_dpp v228, v94, v150 row_shl:15 row_mask:0xf bank_mask:0xf bound_ctrl:1
	v_fmac_f32_dpp v229, v95, v151 row_shl:15 row_mask:0xf bank_mask:0xf bound_ctrl:1
	v_fmac_f32_dpp v230, v96, v152 row_shl:15 row_mask:0xf bank_mask:0xf bound_ctrl:1
	v_fmac_f32_dpp v231, v97, v153 row_shl:15 row_mask:0xf bank_mask:0xf bound_ctrl:1
	v_fmac_f32_dpp v224, v118, v130 row_shl:14 row_mask:0xf bank_mask:0xf bound_ctrl:1
	v_fmac_f32_dpp v225, v119, v131 row_shl:14 row_mask:0xf bank_mask:0xf bound_ctrl:1
	v_fmac_f32_dpp v226, v120, v132 row_shl:14 row_mask:0xf bank_mask:0xf bound_ctrl:1
	v_fmac_f32_dpp v227, v121, v133 row_shl:14 row_mask:0xf bank_mask:0xf bound_ctrl:1
	v_fmac_f32_dpp v228, v94, v146 row_shl:14 row_mask:0xf bank_mask:0xf bound_ctrl:1
	v_fmac_f32_dpp v229, v95, v147 row_shl:14 row_mask:0xf bank_mask:0xf bound_ctrl:1
	v_fmac_f32_dpp v230, v96, v148 row_shl:14 row_mask:0xf bank_mask:0xf bound_ctrl:1
	v_fmac_f32_dpp v231, v97, v149 row_shl:14 row_mask:0xf bank_mask:0xf bound_ctrl:1
	v_pk_mul_f32 v[232:233], v[224:225], s[48:49] op_sel_hi:[1,0]
	v_pk_mul_f32 v[234:235], v[226:227], s[48:49] op_sel_hi:[1,0]
	v_exp_f32_e32 v232, v232
	v_exp_f32_e32 v233, v233
	v_exp_f32_e32 v234, v234
	v_exp_f32_e32 v235, v235
	v_pk_add_f32 v[232:233], v[232:233], 1.0 op_sel_hi:[1,0]
	v_pk_add_f32 v[234:235], v[234:235], 1.0 op_sel_hi:[1,0]
	v_rcp_f32_e32 v232, v232
	v_rcp_f32_e32 v233, v233
	v_rcp_f32_e32 v234, v234
	v_rcp_f32_e32 v235, v235
	v_lshl_add_u64 v[220:221], v[220:221], 0, s[96:97]
	v_pk_mul_f32 v[224:225], v[224:225], v[232:233]
	v_pk_mul_f32 v[226:227], v[226:227], v[234:235]
	v_pk_mul_f32 v[224:225], v[224:225], v[228:229]
	v_pk_mul_f32 v[226:227], v[226:227], v[230:231]
	v_cvt_pk_bf16_f32 v168, v224, v225
	v_cvt_pk_bf16_f32 v169, v226, v227
	global_store_dwordx2 v[220:221], v[168:169], off
	s_add_u32 s94, s26, s85
	s_addc_u32 s95, s27, 0
	v_lshl_add_u64 v[222:223], s[94:95], 0, v[216:217]
	v_lshl_add_u64 v[246:247], s[94:95], 0, v[218:219]
	s_and_saveexec_b64 s[46:47], s[6:7]
	global_store_dwordx4 v[222:223], v[90:93], off
	global_store_dwordx4 v[246:247], v[70:73], off
	s_or_b64 exec, exec, s[46:47]
	v_pk_fma_f32 v[224:225], v[90:91], v[138:139], v[142:143]
	v_pk_fma_f32 v[226:227], v[92:93], v[140:141], v[144:145]
	v_pk_fma_f32 v[228:229], v[70:71], v[154:155], v[158:159]
	v_pk_fma_f32 v[230:231], v[72:73], v[156:157], v[160:161]
	v_fmac_f32_dpp v224, v90, v134 row_shr:1 row_mask:0xf bank_mask:0xf bound_ctrl:1
	v_fmac_f32_dpp v225, v91, v135 row_shr:1 row_mask:0xf bank_mask:0xf bound_ctrl:1
	v_fmac_f32_dpp v226, v92, v136 row_shr:1 row_mask:0xf bank_mask:0xf bound_ctrl:1
	v_fmac_f32_dpp v227, v93, v137 row_shr:1 row_mask:0xf bank_mask:0xf bound_ctrl:1
	v_fmac_f32_dpp v228, v70, v150 row_shr:1 row_mask:0xf bank_mask:0xf bound_ctrl:1
	v_fmac_f32_dpp v229, v71, v151 row_shr:1 row_mask:0xf bank_mask:0xf bound_ctrl:1
	v_fmac_f32_dpp v230, v72, v152 row_shr:1 row_mask:0xf bank_mask:0xf bound_ctrl:1
	v_fmac_f32_dpp v231, v73, v153 row_shr:1 row_mask:0xf bank_mask:0xf bound_ctrl:1
	v_fmac_f32_dpp v224, v90, v130 row_shr:2 row_mask:0xf bank_mask:0xf bound_ctrl:1
	v_fmac_f32_dpp v225, v91, v131 row_shr:2 row_mask:0xf bank_mask:0xf bound_ctrl:1
	v_fmac_f32_dpp v226, v92, v132 row_shr:2 row_mask:0xf bank_mask:0xf bound_ctrl:1
	v_fmac_f32_dpp v227, v93, v133 row_shr:2 row_mask:0xf bank_mask:0xf bound_ctrl:1
	v_fmac_f32_dpp v228, v70, v146 row_shr:2 row_mask:0xf bank_mask:0xf bound_ctrl:1
	v_fmac_f32_dpp v229, v71, v147 row_shr:2 row_mask:0xf bank_mask:0xf bound_ctrl:1
	v_fmac_f32_dpp v230, v72, v148 row_shr:2 row_mask:0xf bank_mask:0xf bound_ctrl:1
	v_fmac_f32_dpp v231, v73, v149 row_shr:2 row_mask:0xf bank_mask:0xf bound_ctrl:1
	v_fmac_f32_dpp v224, v106, v134 row_shl:15 row_mask:0xf bank_mask:0xf bound_ctrl:1
	v_fmac_f32_dpp v225, v107, v135 row_shl:15 row_mask:0xf bank_mask:0xf bound_ctrl:1
	v_fmac_f32_dpp v226, v108, v136 row_shl:15 row_mask:0xf bank_mask:0xf bound_ctrl:1
	v_fmac_f32_dpp v227, v109, v137 row_shl:15 row_mask:0xf bank_mask:0xf bound_ctrl:1
	v_fmac_f32_dpp v228, v78, v150 row_shl:15 row_mask:0xf bank_mask:0xf bound_ctrl:1
	v_fmac_f32_dpp v229, v79, v151 row_shl:15 row_mask:0xf bank_mask:0xf bound_ctrl:1
	v_fmac_f32_dpp v230, v80, v152 row_shl:15 row_mask:0xf bank_mask:0xf bound_ctrl:1
	v_fmac_f32_dpp v231, v81, v153 row_shl:15 row_mask:0xf bank_mask:0xf bound_ctrl:1
	v_fmac_f32_dpp v224, v106, v130 row_shl:14 row_mask:0xf bank_mask:0xf bound_ctrl:1
	v_fmac_f32_dpp v225, v107, v131 row_shl:14 row_mask:0xf bank_mask:0xf bound_ctrl:1
	v_fmac_f32_dpp v226, v108, v132 row_shl:14 row_mask:0xf bank_mask:0xf bound_ctrl:1
	v_fmac_f32_dpp v227, v109, v133 row_shl:14 row_mask:0xf bank_mask:0xf bound_ctrl:1
	v_fmac_f32_dpp v228, v78, v146 row_shl:14 row_mask:0xf bank_mask:0xf bound_ctrl:1
	v_fmac_f32_dpp v229, v79, v147 row_shl:14 row_mask:0xf bank_mask:0xf bound_ctrl:1
	v_fmac_f32_dpp v230, v80, v148 row_shl:14 row_mask:0xf bank_mask:0xf bound_ctrl:1
	v_fmac_f32_dpp v231, v81, v149 row_shl:14 row_mask:0xf bank_mask:0xf bound_ctrl:1
	v_pk_mul_f32 v[232:233], v[224:225], s[48:49] op_sel_hi:[1,0]
	v_pk_mul_f32 v[234:235], v[226:227], s[48:49] op_sel_hi:[1,0]
	v_exp_f32_e32 v232, v232
	v_exp_f32_e32 v233, v233
	v_exp_f32_e32 v234, v234
	v_exp_f32_e32 v235, v235
	v_pk_add_f32 v[232:233], v[232:233], 1.0 op_sel_hi:[1,0]
	v_pk_add_f32 v[234:235], v[234:235], 1.0 op_sel_hi:[1,0]
	v_rcp_f32_e32 v232, v232
	v_rcp_f32_e32 v233, v233
	v_rcp_f32_e32 v234, v234
	v_rcp_f32_e32 v235, v235
	v_lshl_add_u64 v[220:221], v[220:221], 0, s[96:97]
	v_pk_mul_f32 v[224:225], v[224:225], v[232:233]
	v_pk_mul_f32 v[226:227], v[226:227], v[234:235]
	v_pk_mul_f32 v[224:225], v[224:225], v[228:229]
	v_pk_mul_f32 v[226:227], v[226:227], v[230:231]
	v_cvt_pk_bf16_f32 v168, v224, v225
	v_cvt_pk_bf16_f32 v169, v226, v227
	global_store_dwordx2 v[220:221], v[168:169], off
	s_add_i32 s84, s39, 2
	s_mul_i32 s85, s84, 0xb0000
	s_add_u32 s94, s22, s85
	s_addc_u32 s95, s23, 0
	v_lshl_add_u64 v[220:221], s[94:95], 0, v[210:211]
	s_mul_i32 s85, s84, 0x16000
	s_add_u32 s94, s24, s85
	s_addc_u32 s95, s25, 0
	v_lshl_add_u64 v[222:223], s[94:95], 0, v[212:213]
	v_lshl_add_u64 v[246:247], s[94:95], 0, v[214:215]
	s_and_saveexec_b64 s[46:47], s[4:5]
	global_store_dwordx4 v[222:223], v[62:65], off
	global_store_dwordx4 v[246:247], v[46:49], off
	s_or_b64 exec, exec, s[46:47]
	v_pk_fma_f32 v[224:225], v[62:63], v[138:139], v[142:143]
	v_pk_fma_f32 v[226:227], v[64:65], v[140:141], v[144:145]
	v_pk_fma_f32 v[228:229], v[46:47], v[154:155], v[158:159]
	v_pk_fma_f32 v[230:231], v[48:49], v[156:157], v[160:161]
	v_fmac_f32_dpp v224, v62, v134 row_shr:1 row_mask:0xf bank_mask:0xf bound_ctrl:1
	v_fmac_f32_dpp v225, v63, v135 row_shr:1 row_mask:0xf bank_mask:0xf bound_ctrl:1
	v_fmac_f32_dpp v226, v64, v136 row_shr:1 row_mask:0xf bank_mask:0xf bound_ctrl:1
	v_fmac_f32_dpp v227, v65, v137 row_shr:1 row_mask:0xf bank_mask:0xf bound_ctrl:1
	v_fmac_f32_dpp v228, v46, v150 row_shr:1 row_mask:0xf bank_mask:0xf bound_ctrl:1
	v_fmac_f32_dpp v229, v47, v151 row_shr:1 row_mask:0xf bank_mask:0xf bound_ctrl:1
	v_fmac_f32_dpp v230, v48, v152 row_shr:1 row_mask:0xf bank_mask:0xf bound_ctrl:1
	v_fmac_f32_dpp v231, v49, v153 row_shr:1 row_mask:0xf bank_mask:0xf bound_ctrl:1
	v_fmac_f32_dpp v224, v62, v130 row_shr:2 row_mask:0xf bank_mask:0xf bound_ctrl:1
	v_fmac_f32_dpp v225, v63, v131 row_shr:2 row_mask:0xf bank_mask:0xf bound_ctrl:1
	v_fmac_f32_dpp v226, v64, v132 row_shr:2 row_mask:0xf bank_mask:0xf bound_ctrl:1
	v_fmac_f32_dpp v227, v65, v133 row_shr:2 row_mask:0xf bank_mask:0xf bound_ctrl:1
	v_fmac_f32_dpp v228, v46, v146 row_shr:2 row_mask:0xf bank_mask:0xf bound_ctrl:1
	v_fmac_f32_dpp v229, v47, v147 row_shr:2 row_mask:0xf bank_mask:0xf bound_ctrl:1
	v_fmac_f32_dpp v230, v48, v148 row_shr:2 row_mask:0xf bank_mask:0xf bound_ctrl:1
	v_fmac_f32_dpp v231, v49, v149 row_shr:2 row_mask:0xf bank_mask:0xf bound_ctrl:1
	v_pk_mul_f32 v[232:233], v[224:225], s[48:49] op_sel_hi:[1,0]
	v_pk_mul_f32 v[234:235], v[226:227], s[48:49] op_sel_hi:[1,0]
	v_exp_f32_e32 v232, v232
	v_exp_f32_e32 v233, v233
	v_exp_f32_e32 v234, v234
	v_exp_f32_e32 v235, v235
	v_pk_add_f32 v[232:233], v[232:233], 1.0 op_sel_hi:[1,0]
	v_pk_add_f32 v[234:235], v[234:235], 1.0 op_sel_hi:[1,0]
	v_rcp_f32_e32 v232, v232
	v_rcp_f32_e32 v233, v233
	v_rcp_f32_e32 v234, v234
	v_rcp_f32_e32 v235, v235
	v_pk_mul_f32 v[224:225], v[224:225], v[232:233]
	v_pk_mul_f32 v[226:227], v[226:227], v[234:235]
	v_pk_mul_f32 v[224:225], v[224:225], v[228:229]
	v_pk_mul_f32 v[226:227], v[226:227], v[230:231]
	v_cvt_pk_bf16_f32 v168, v224, v225
	v_cvt_pk_bf16_f32 v169, v226, v227
	s_and_saveexec_b64 s[46:47], s[8:9]
	global_store_dwordx2 v[220:221], v[168:169], off
	s_or_b64 exec, exec, s[46:47]
	v_pk_fma_f32 v[224:225], v[54:55], v[138:139], v[142:143]
	v_pk_fma_f32 v[226:227], v[56:57], v[140:141], v[144:145]
	v_pk_fma_f32 v[228:229], v[30:31], v[154:155], v[158:159]
	v_pk_fma_f32 v[230:231], v[32:33], v[156:157], v[160:161]
	v_fmac_f32_dpp v224, v54, v134 row_shr:1 row_mask:0xf bank_mask:0xf bound_ctrl:1
	v_fmac_f32_dpp v225, v55, v135 row_shr:1 row_mask:0xf bank_mask:0xf bound_ctrl:1
	v_fmac_f32_dpp v226, v56, v136 row_shr:1 row_mask:0xf bank_mask:0xf bound_ctrl:1
	v_fmac_f32_dpp v227, v57, v137 row_shr:1 row_mask:0xf bank_mask:0xf bound_ctrl:1
	v_fmac_f32_dpp v228, v30, v150 row_shr:1 row_mask:0xf bank_mask:0xf bound_ctrl:1
	v_fmac_f32_dpp v229, v31, v151 row_shr:1 row_mask:0xf bank_mask:0xf bound_ctrl:1
	v_fmac_f32_dpp v230, v32, v152 row_shr:1 row_mask:0xf bank_mask:0xf bound_ctrl:1
	v_fmac_f32_dpp v231, v33, v153 row_shr:1 row_mask:0xf bank_mask:0xf bound_ctrl:1
	v_fmac_f32_dpp v224, v54, v130 row_shr:2 row_mask:0xf bank_mask:0xf bound_ctrl:1
	v_fmac_f32_dpp v225, v55, v131 row_shr:2 row_mask:0xf bank_mask:0xf bound_ctrl:1
	v_fmac_f32_dpp v226, v56, v132 row_shr:2 row_mask:0xf bank_mask:0xf bound_ctrl:1
	v_fmac_f32_dpp v227, v57, v133 row_shr:2 row_mask:0xf bank_mask:0xf bound_ctrl:1
	v_fmac_f32_dpp v228, v30, v146 row_shr:2 row_mask:0xf bank_mask:0xf bound_ctrl:1
	v_fmac_f32_dpp v229, v31, v147 row_shr:2 row_mask:0xf bank_mask:0xf bound_ctrl:1
	v_fmac_f32_dpp v230, v32, v148 row_shr:2 row_mask:0xf bank_mask:0xf bound_ctrl:1
	v_fmac_f32_dpp v231, v33, v149 row_shr:2 row_mask:0xf bank_mask:0xf bound_ctrl:1
	v_fmac_f32_dpp v224, v62, v134 row_shl:15 row_mask:0xf bank_mask:0xf bound_ctrl:1
	v_fmac_f32_dpp v225, v63, v135 row_shl:15 row_mask:0xf bank_mask:0xf bound_ctrl:1
	v_fmac_f32_dpp v226, v64, v136 row_shl:15 row_mask:0xf bank_mask:0xf bound_ctrl:1
	v_fmac_f32_dpp v227, v65, v137 row_shl:15 row_mask:0xf bank_mask:0xf bound_ctrl:1
	v_fmac_f32_dpp v228, v46, v150 row_shl:15 row_mask:0xf bank_mask:0xf bound_ctrl:1
	v_fmac_f32_dpp v229, v47, v151 row_shl:15 row_mask:0xf bank_mask:0xf bound_ctrl:1
	v_fmac_f32_dpp v230, v48, v152 row_shl:15 row_mask:0xf bank_mask:0xf bound_ctrl:1
	v_fmac_f32_dpp v231, v49, v153 row_shl:15 row_mask:0xf bank_mask:0xf bound_ctrl:1
	v_fmac_f32_dpp v224, v62, v130 row_shl:14 row_mask:0xf bank_mask:0xf bound_ctrl:1
	v_fmac_f32_dpp v225, v63, v131 row_shl:14 row_mask:0xf bank_mask:0xf bound_ctrl:1
	v_fmac_f32_dpp v226, v64, v132 row_shl:14 row_mask:0xf bank_mask:0xf bound_ctrl:1
	v_fmac_f32_dpp v227, v65, v133 row_shl:14 row_mask:0xf bank_mask:0xf bound_ctrl:1
	v_fmac_f32_dpp v228, v46, v146 row_shl:14 row_mask:0xf bank_mask:0xf bound_ctrl:1
	v_fmac_f32_dpp v229, v47, v147 row_shl:14 row_mask:0xf bank_mask:0xf bound_ctrl:1
	v_fmac_f32_dpp v230, v48, v148 row_shl:14 row_mask:0xf bank_mask:0xf bound_ctrl:1
	v_fmac_f32_dpp v231, v49, v149 row_shl:14 row_mask:0xf bank_mask:0xf bound_ctrl:1
	v_pk_mul_f32 v[232:233], v[224:225], s[48:49] op_sel_hi:[1,0]
	v_pk_mul_f32 v[234:235], v[226:227], s[48:49] op_sel_hi:[1,0]
	v_exp_f32_e32 v232, v232
	v_exp_f32_e32 v233, v233
	v_exp_f32_e32 v234, v234
	v_exp_f32_e32 v235, v235
	v_pk_add_f32 v[232:233], v[232:233], 1.0 op_sel_hi:[1,0]
	v_pk_add_f32 v[234:235], v[234:235], 1.0 op_sel_hi:[1,0]
	v_rcp_f32_e32 v232, v232
	v_rcp_f32_e32 v233, v233
	v_rcp_f32_e32 v234, v234
	v_rcp_f32_e32 v235, v235
	v_lshl_add_u64 v[220:221], v[220:221], 0, s[96:97]
	v_pk_mul_f32 v[224:225], v[224:225], v[232:233]
	v_pk_mul_f32 v[226:227], v[226:227], v[234:235]
	v_pk_mul_f32 v[224:225], v[224:225], v[228:229]
	v_pk_mul_f32 v[226:227], v[226:227], v[230:231]
	v_cvt_pk_bf16_f32 v168, v224, v225
	v_cvt_pk_bf16_f32 v169, v226, v227
	global_store_dwordx2 v[220:221], v[168:169], off
	v_pk_fma_f32 v[224:225], v[42:43], v[138:139], v[142:143]
	v_pk_fma_f32 v[226:227], v[44:45], v[140:141], v[144:145]
	v_pk_fma_f32 v[228:229], v[14:15], v[154:155], v[158:159]
	v_pk_fma_f32 v[230:231], v[16:17], v[156:157], v[160:161]
	v_fmac_f32_dpp v224, v42, v134 row_shr:1 row_mask:0xf bank_mask:0xf bound_ctrl:1
	v_fmac_f32_dpp v225, v43, v135 row_shr:1 row_mask:0xf bank_mask:0xf bound_ctrl:1
	v_fmac_f32_dpp v226, v44, v136 row_shr:1 row_mask:0xf bank_mask:0xf bound_ctrl:1
	v_fmac_f32_dpp v227, v45, v137 row_shr:1 row_mask:0xf bank_mask:0xf bound_ctrl:1
	v_fmac_f32_dpp v228, v14, v150 row_shr:1 row_mask:0xf bank_mask:0xf bound_ctrl:1
	v_fmac_f32_dpp v229, v15, v151 row_shr:1 row_mask:0xf bank_mask:0xf bound_ctrl:1
	v_fmac_f32_dpp v230, v16, v152 row_shr:1 row_mask:0xf bank_mask:0xf bound_ctrl:1
	v_fmac_f32_dpp v231, v17, v153 row_shr:1 row_mask:0xf bank_mask:0xf bound_ctrl:1
	v_fmac_f32_dpp v224, v42, v130 row_shr:2 row_mask:0xf bank_mask:0xf bound_ctrl:1
	v_fmac_f32_dpp v225, v43, v131 row_shr:2 row_mask:0xf bank_mask:0xf bound_ctrl:1
	v_fmac_f32_dpp v226, v44, v132 row_shr:2 row_mask:0xf bank_mask:0xf bound_ctrl:1
	v_fmac_f32_dpp v227, v45, v133 row_shr:2 row_mask:0xf bank_mask:0xf bound_ctrl:1
	v_fmac_f32_dpp v228, v14, v146 row_shr:2 row_mask:0xf bank_mask:0xf bound_ctrl:1
	v_fmac_f32_dpp v229, v15, v147 row_shr:2 row_mask:0xf bank_mask:0xf bound_ctrl:1
	v_fmac_f32_dpp v230, v16, v148 row_shr:2 row_mask:0xf bank_mask:0xf bound_ctrl:1
	v_fmac_f32_dpp v231, v17, v149 row_shr:2 row_mask:0xf bank_mask:0xf bound_ctrl:1
	v_fmac_f32_dpp v224, v54, v134 row_shl:15 row_mask:0xf bank_mask:0xf bound_ctrl:1
	v_fmac_f32_dpp v225, v55, v135 row_shl:15 row_mask:0xf bank_mask:0xf bound_ctrl:1
	v_fmac_f32_dpp v226, v56, v136 row_shl:15 row_mask:0xf bank_mask:0xf bound_ctrl:1
	v_fmac_f32_dpp v227, v57, v137 row_shl:15 row_mask:0xf bank_mask:0xf bound_ctrl:1
	v_fmac_f32_dpp v228, v30, v150 row_shl:15 row_mask:0xf bank_mask:0xf bound_ctrl:1
	v_fmac_f32_dpp v229, v31, v151 row_shl:15 row_mask:0xf bank_mask:0xf bound_ctrl:1
	v_fmac_f32_dpp v230, v32, v152 row_shl:15 row_mask:0xf bank_mask:0xf bound_ctrl:1
	v_fmac_f32_dpp v231, v33, v153 row_shl:15 row_mask:0xf bank_mask:0xf bound_ctrl:1
	v_fmac_f32_dpp v224, v54, v130 row_shl:14 row_mask:0xf bank_mask:0xf bound_ctrl:1
	v_fmac_f32_dpp v225, v55, v131 row_shl:14 row_mask:0xf bank_mask:0xf bound_ctrl:1
	v_fmac_f32_dpp v226, v56, v132 row_shl:14 row_mask:0xf bank_mask:0xf bound_ctrl:1
	v_fmac_f32_dpp v227, v57, v133 row_shl:14 row_mask:0xf bank_mask:0xf bound_ctrl:1
	v_fmac_f32_dpp v228, v30, v146 row_shl:14 row_mask:0xf bank_mask:0xf bound_ctrl:1
	v_fmac_f32_dpp v229, v31, v147 row_shl:14 row_mask:0xf bank_mask:0xf bound_ctrl:1
	v_fmac_f32_dpp v230, v32, v148 row_shl:14 row_mask:0xf bank_mask:0xf bound_ctrl:1
	v_fmac_f32_dpp v231, v33, v149 row_shl:14 row_mask:0xf bank_mask:0xf bound_ctrl:1
	v_pk_mul_f32 v[232:233], v[224:225], s[48:49] op_sel_hi:[1,0]
	v_pk_mul_f32 v[234:235], v[226:227], s[48:49] op_sel_hi:[1,0]
	v_exp_f32_e32 v232, v232
	v_exp_f32_e32 v233, v233
	v_exp_f32_e32 v234, v234
	v_exp_f32_e32 v235, v235
	v_pk_add_f32 v[232:233], v[232:233], 1.0 op_sel_hi:[1,0]
	v_pk_add_f32 v[234:235], v[234:235], 1.0 op_sel_hi:[1,0]
	v_rcp_f32_e32 v232, v232
	v_rcp_f32_e32 v233, v233
	v_rcp_f32_e32 v234, v234
	v_rcp_f32_e32 v235, v235
	v_lshl_add_u64 v[220:221], v[220:221], 0, s[96:97]
	v_pk_mul_f32 v[224:225], v[224:225], v[232:233]
	v_pk_mul_f32 v[226:227], v[226:227], v[234:235]
	v_pk_mul_f32 v[224:225], v[224:225], v[228:229]
	v_pk_mul_f32 v[226:227], v[226:227], v[230:231]
	v_cvt_pk_bf16_f32 v168, v224, v225
	v_cvt_pk_bf16_f32 v169, v226, v227
	global_store_dwordx2 v[220:221], v[168:169], off
	s_add_u32 s94, s26, s85
	s_addc_u32 s95, s27, 0
	v_lshl_add_u64 v[222:223], s[94:95], 0, v[216:217]
	v_lshl_add_u64 v[246:247], s[94:95], 0, v[218:219]
	s_and_saveexec_b64 s[46:47], s[6:7]
	global_store_dwordx4 v[222:223], v[26:29], off
	global_store_dwordx4 v[246:247], v[6:9], off
	s_or_b64 exec, exec, s[46:47]
	v_pk_fma_f32 v[224:225], v[26:27], v[138:139], v[142:143]
	v_pk_fma_f32 v[226:227], v[28:29], v[140:141], v[144:145]
	v_pk_fma_f32 v[228:229], v[6:7], v[154:155], v[158:159]
	v_pk_fma_f32 v[230:231], v[8:9], v[156:157], v[160:161]
	v_fmac_f32_dpp v224, v26, v134 row_shr:1 row_mask:0xf bank_mask:0xf bound_ctrl:1
	v_fmac_f32_dpp v225, v27, v135 row_shr:1 row_mask:0xf bank_mask:0xf bound_ctrl:1
	v_fmac_f32_dpp v226, v28, v136 row_shr:1 row_mask:0xf bank_mask:0xf bound_ctrl:1
	v_fmac_f32_dpp v227, v29, v137 row_shr:1 row_mask:0xf bank_mask:0xf bound_ctrl:1
	v_fmac_f32_dpp v228, v6, v150 row_shr:1 row_mask:0xf bank_mask:0xf bound_ctrl:1
	v_fmac_f32_dpp v229, v7, v151 row_shr:1 row_mask:0xf bank_mask:0xf bound_ctrl:1
	v_fmac_f32_dpp v230, v8, v152 row_shr:1 row_mask:0xf bank_mask:0xf bound_ctrl:1
	v_fmac_f32_dpp v231, v9, v153 row_shr:1 row_mask:0xf bank_mask:0xf bound_ctrl:1
	v_fmac_f32_dpp v224, v26, v130 row_shr:2 row_mask:0xf bank_mask:0xf bound_ctrl:1
	v_fmac_f32_dpp v225, v27, v131 row_shr:2 row_mask:0xf bank_mask:0xf bound_ctrl:1
	v_fmac_f32_dpp v226, v28, v132 row_shr:2 row_mask:0xf bank_mask:0xf bound_ctrl:1
	v_fmac_f32_dpp v227, v29, v133 row_shr:2 row_mask:0xf bank_mask:0xf bound_ctrl:1
	v_fmac_f32_dpp v228, v6, v146 row_shr:2 row_mask:0xf bank_mask:0xf bound_ctrl:1
	v_fmac_f32_dpp v229, v7, v147 row_shr:2 row_mask:0xf bank_mask:0xf bound_ctrl:1
	v_fmac_f32_dpp v230, v8, v148 row_shr:2 row_mask:0xf bank_mask:0xf bound_ctrl:1
	v_fmac_f32_dpp v231, v9, v149 row_shr:2 row_mask:0xf bank_mask:0xf bound_ctrl:1
	v_fmac_f32_dpp v224, v42, v134 row_shl:15 row_mask:0xf bank_mask:0xf bound_ctrl:1
	v_fmac_f32_dpp v225, v43, v135 row_shl:15 row_mask:0xf bank_mask:0xf bound_ctrl:1
	v_fmac_f32_dpp v226, v44, v136 row_shl:15 row_mask:0xf bank_mask:0xf bound_ctrl:1
	v_fmac_f32_dpp v227, v45, v137 row_shl:15 row_mask:0xf bank_mask:0xf bound_ctrl:1
	v_fmac_f32_dpp v228, v14, v150 row_shl:15 row_mask:0xf bank_mask:0xf bound_ctrl:1
	v_fmac_f32_dpp v229, v15, v151 row_shl:15 row_mask:0xf bank_mask:0xf bound_ctrl:1
	v_fmac_f32_dpp v230, v16, v152 row_shl:15 row_mask:0xf bank_mask:0xf bound_ctrl:1
	v_fmac_f32_dpp v231, v17, v153 row_shl:15 row_mask:0xf bank_mask:0xf bound_ctrl:1
	v_fmac_f32_dpp v224, v42, v130 row_shl:14 row_mask:0xf bank_mask:0xf bound_ctrl:1
	v_fmac_f32_dpp v225, v43, v131 row_shl:14 row_mask:0xf bank_mask:0xf bound_ctrl:1
	v_fmac_f32_dpp v226, v44, v132 row_shl:14 row_mask:0xf bank_mask:0xf bound_ctrl:1
	v_fmac_f32_dpp v227, v45, v133 row_shl:14 row_mask:0xf bank_mask:0xf bound_ctrl:1
	v_fmac_f32_dpp v228, v14, v146 row_shl:14 row_mask:0xf bank_mask:0xf bound_ctrl:1
	v_fmac_f32_dpp v229, v15, v147 row_shl:14 row_mask:0xf bank_mask:0xf bound_ctrl:1
	v_fmac_f32_dpp v230, v16, v148 row_shl:14 row_mask:0xf bank_mask:0xf bound_ctrl:1
	v_fmac_f32_dpp v231, v17, v149 row_shl:14 row_mask:0xf bank_mask:0xf bound_ctrl:1
	v_pk_mul_f32 v[232:233], v[224:225], s[48:49] op_sel_hi:[1,0]
	v_pk_mul_f32 v[234:235], v[226:227], s[48:49] op_sel_hi:[1,0]
	v_exp_f32_e32 v232, v232
	v_exp_f32_e32 v233, v233
	v_exp_f32_e32 v234, v234
	v_exp_f32_e32 v235, v235
	v_pk_add_f32 v[232:233], v[232:233], 1.0 op_sel_hi:[1,0]
	v_pk_add_f32 v[234:235], v[234:235], 1.0 op_sel_hi:[1,0]
	v_rcp_f32_e32 v232, v232
	v_rcp_f32_e32 v233, v233
	v_rcp_f32_e32 v234, v234
	v_rcp_f32_e32 v235, v235
	v_lshl_add_u64 v[220:221], v[220:221], 0, s[96:97]
	v_pk_mul_f32 v[224:225], v[224:225], v[232:233]
	v_pk_mul_f32 v[226:227], v[226:227], v[234:235]
	v_pk_mul_f32 v[224:225], v[224:225], v[228:229]
	v_pk_mul_f32 v[226:227], v[226:227], v[230:231]
	v_cvt_pk_bf16_f32 v168, v224, v225
	v_cvt_pk_bf16_f32 v169, v226, v227
	global_store_dwordx2 v[220:221], v[168:169], off
	s_add_i32 s84, s39, 0
	s_mul_i32 s85, s84, 0xb0000
	s_add_u32 s94, s22, s85
	s_addc_u32 s95, s23, 0
	v_lshl_add_u64 v[220:221], s[94:95], 0, v[210:211]
	s_mul_i32 s85, s84, 0x16000
	s_add_u32 s94, s24, s85
	s_addc_u32 s95, s25, 0
	v_lshl_add_u64 v[222:223], s[94:95], 0, v[212:213]
	v_lshl_add_u64 v[246:247], s[94:95], 0, v[214:215]
	s_and_saveexec_b64 s[46:47], s[4:5]
	global_store_dwordx4 v[222:223], v[122:125], off offset:64
	global_store_dwordx4 v[246:247], v[102:105], off offset:64
	s_or_b64 exec, exec, s[46:47]
	v_pk_fma_f32 v[224:225], v[122:123], v[186:187], v[190:191]
	v_pk_fma_f32 v[226:227], v[124:125], v[188:189], v[192:193]
	v_pk_fma_f32 v[228:229], v[102:103], v[202:203], v[206:207]
	v_pk_fma_f32 v[230:231], v[104:105], v[204:205], v[208:209]
	v_fmac_f32_dpp v224, v122, v182 row_shr:1 row_mask:0xf bank_mask:0xf bound_ctrl:1
	v_fmac_f32_dpp v225, v123, v183 row_shr:1 row_mask:0xf bank_mask:0xf bound_ctrl:1
	v_fmac_f32_dpp v226, v124, v184 row_shr:1 row_mask:0xf bank_mask:0xf bound_ctrl:1
	v_fmac_f32_dpp v227, v125, v185 row_shr:1 row_mask:0xf bank_mask:0xf bound_ctrl:1
	v_fmac_f32_dpp v228, v102, v198 row_shr:1 row_mask:0xf bank_mask:0xf bound_ctrl:1
	v_fmac_f32_dpp v229, v103, v199 row_shr:1 row_mask:0xf bank_mask:0xf bound_ctrl:1
	v_fmac_f32_dpp v230, v104, v200 row_shr:1 row_mask:0xf bank_mask:0xf bound_ctrl:1
	v_fmac_f32_dpp v231, v105, v201 row_shr:1 row_mask:0xf bank_mask:0xf bound_ctrl:1
	v_fmac_f32_dpp v224, v122, v178 row_shr:2 row_mask:0xf bank_mask:0xf bound_ctrl:1
	v_fmac_f32_dpp v225, v123, v179 row_shr:2 row_mask:0xf bank_mask:0xf bound_ctrl:1
	v_fmac_f32_dpp v226, v124, v180 row_shr:2 row_mask:0xf bank_mask:0xf bound_ctrl:1
	v_fmac_f32_dpp v227, v125, v181 row_shr:2 row_mask:0xf bank_mask:0xf bound_ctrl:1
	v_fmac_f32_dpp v228, v102, v194 row_shr:2 row_mask:0xf bank_mask:0xf bound_ctrl:1
	v_fmac_f32_dpp v229, v103, v195 row_shr:2 row_mask:0xf bank_mask:0xf bound_ctrl:1
	v_fmac_f32_dpp v230, v104, v196 row_shr:2 row_mask:0xf bank_mask:0xf bound_ctrl:1
	v_fmac_f32_dpp v231, v105, v197 row_shr:2 row_mask:0xf bank_mask:0xf bound_ctrl:1
	v_pk_mul_f32 v[232:233], v[224:225], s[48:49] op_sel_hi:[1,0]
	v_pk_mul_f32 v[234:235], v[226:227], s[48:49] op_sel_hi:[1,0]
	v_exp_f32_e32 v232, v232
	v_exp_f32_e32 v233, v233
	v_exp_f32_e32 v234, v234
	v_exp_f32_e32 v235, v235
	v_pk_add_f32 v[232:233], v[232:233], 1.0 op_sel_hi:[1,0]
	v_pk_add_f32 v[234:235], v[234:235], 1.0 op_sel_hi:[1,0]
	v_rcp_f32_e32 v232, v232
	v_rcp_f32_e32 v233, v233
	v_rcp_f32_e32 v234, v234
	v_rcp_f32_e32 v235, v235
	v_pk_mul_f32 v[224:225], v[224:225], v[232:233]
	v_pk_mul_f32 v[226:227], v[226:227], v[234:235]
	v_pk_mul_f32 v[224:225], v[224:225], v[228:229]
	v_pk_mul_f32 v[226:227], v[226:227], v[230:231]
	v_cvt_pk_bf16_f32 v168, v224, v225
	v_cvt_pk_bf16_f32 v169, v226, v227
	s_and_saveexec_b64 s[46:47], s[8:9]
	global_store_dwordx2 v[220:221], v[168:169], off offset:32
	s_or_b64 exec, exec, s[46:47]
	v_pk_fma_f32 v[224:225], v[114:115], v[186:187], v[190:191]
	v_pk_fma_f32 v[226:227], v[116:117], v[188:189], v[192:193]
	v_pk_fma_f32 v[228:229], v[86:87], v[202:203], v[206:207]
	v_pk_fma_f32 v[230:231], v[88:89], v[204:205], v[208:209]
	v_fmac_f32_dpp v224, v114, v182 row_shr:1 row_mask:0xf bank_mask:0xf bound_ctrl:1
	v_fmac_f32_dpp v225, v115, v183 row_shr:1 row_mask:0xf bank_mask:0xf bound_ctrl:1
	v_fmac_f32_dpp v226, v116, v184 row_shr:1 row_mask:0xf bank_mask:0xf bound_ctrl:1
	v_fmac_f32_dpp v227, v117, v185 row_shr:1 row_mask:0xf bank_mask:0xf bound_ctrl:1
	v_fmac_f32_dpp v228, v86, v198 row_shr:1 row_mask:0xf bank_mask:0xf bound_ctrl:1
	v_fmac_f32_dpp v229, v87, v199 row_shr:1 row_mask:0xf bank_mask:0xf bound_ctrl:1
	v_fmac_f32_dpp v230, v88, v200 row_shr:1 row_mask:0xf bank_mask:0xf bound_ctrl:1
	v_fmac_f32_dpp v231, v89, v201 row_shr:1 row_mask:0xf bank_mask:0xf bound_ctrl:1
	v_fmac_f32_dpp v224, v114, v178 row_shr:2 row_mask:0xf bank_mask:0xf bound_ctrl:1
	v_fmac_f32_dpp v225, v115, v179 row_shr:2 row_mask:0xf bank_mask:0xf bound_ctrl:1
	v_fmac_f32_dpp v226, v116, v180 row_shr:2 row_mask:0xf bank_mask:0xf bound_ctrl:1
	v_fmac_f32_dpp v227, v117, v181 row_shr:2 row_mask:0xf bank_mask:0xf bound_ctrl:1
	v_fmac_f32_dpp v228, v86, v194 row_shr:2 row_mask:0xf bank_mask:0xf bound_ctrl:1
	v_fmac_f32_dpp v229, v87, v195 row_shr:2 row_mask:0xf bank_mask:0xf bound_ctrl:1
	v_fmac_f32_dpp v230, v88, v196 row_shr:2 row_mask:0xf bank_mask:0xf bound_ctrl:1
	v_fmac_f32_dpp v231, v89, v197 row_shr:2 row_mask:0xf bank_mask:0xf bound_ctrl:1
	v_fmac_f32_dpp v224, v122, v182 row_shl:15 row_mask:0xf bank_mask:0xf bound_ctrl:1
	v_fmac_f32_dpp v225, v123, v183 row_shl:15 row_mask:0xf bank_mask:0xf bound_ctrl:1
	v_fmac_f32_dpp v226, v124, v184 row_shl:15 row_mask:0xf bank_mask:0xf bound_ctrl:1
	v_fmac_f32_dpp v227, v125, v185 row_shl:15 row_mask:0xf bank_mask:0xf bound_ctrl:1
	v_fmac_f32_dpp v228, v102, v198 row_shl:15 row_mask:0xf bank_mask:0xf bound_ctrl:1
	v_fmac_f32_dpp v229, v103, v199 row_shl:15 row_mask:0xf bank_mask:0xf bound_ctrl:1
	v_fmac_f32_dpp v230, v104, v200 row_shl:15 row_mask:0xf bank_mask:0xf bound_ctrl:1
	v_fmac_f32_dpp v231, v105, v201 row_shl:15 row_mask:0xf bank_mask:0xf bound_ctrl:1
	v_fmac_f32_dpp v224, v122, v178 row_shl:14 row_mask:0xf bank_mask:0xf bound_ctrl:1
	v_fmac_f32_dpp v225, v123, v179 row_shl:14 row_mask:0xf bank_mask:0xf bound_ctrl:1
	v_fmac_f32_dpp v226, v124, v180 row_shl:14 row_mask:0xf bank_mask:0xf bound_ctrl:1
	v_fmac_f32_dpp v227, v125, v181 row_shl:14 row_mask:0xf bank_mask:0xf bound_ctrl:1
	v_fmac_f32_dpp v228, v102, v194 row_shl:14 row_mask:0xf bank_mask:0xf bound_ctrl:1
	v_fmac_f32_dpp v229, v103, v195 row_shl:14 row_mask:0xf bank_mask:0xf bound_ctrl:1
	v_fmac_f32_dpp v230, v104, v196 row_shl:14 row_mask:0xf bank_mask:0xf bound_ctrl:1
	v_fmac_f32_dpp v231, v105, v197 row_shl:14 row_mask:0xf bank_mask:0xf bound_ctrl:1
	v_pk_mul_f32 v[232:233], v[224:225], s[48:49] op_sel_hi:[1,0]
	v_pk_mul_f32 v[234:235], v[226:227], s[48:49] op_sel_hi:[1,0]
	v_exp_f32_e32 v232, v232
	v_exp_f32_e32 v233, v233
	v_exp_f32_e32 v234, v234
	v_exp_f32_e32 v235, v235
	v_pk_add_f32 v[232:233], v[232:233], 1.0 op_sel_hi:[1,0]
	v_pk_add_f32 v[234:235], v[234:235], 1.0 op_sel_hi:[1,0]
	v_rcp_f32_e32 v232, v232
	v_rcp_f32_e32 v233, v233
	v_rcp_f32_e32 v234, v234
	v_rcp_f32_e32 v235, v235
	v_lshl_add_u64 v[220:221], v[220:221], 0, s[96:97]
	v_pk_mul_f32 v[224:225], v[224:225], v[232:233]
	v_pk_mul_f32 v[226:227], v[226:227], v[234:235]
	v_pk_mul_f32 v[224:225], v[224:225], v[228:229]
	v_pk_mul_f32 v[226:227], v[226:227], v[230:231]
	v_cvt_pk_bf16_f32 v168, v224, v225
	v_cvt_pk_bf16_f32 v169, v226, v227
	global_store_dwordx2 v[220:221], v[168:169], off offset:32
	v_pk_fma_f32 v[224:225], v[98:99], v[186:187], v[190:191]
	v_pk_fma_f32 v[226:227], v[100:101], v[188:189], v[192:193]
	v_pk_fma_f32 v[228:229], v[74:75], v[202:203], v[206:207]
	v_pk_fma_f32 v[230:231], v[76:77], v[204:205], v[208:209]
	v_fmac_f32_dpp v224, v98, v182 row_shr:1 row_mask:0xf bank_mask:0xf bound_ctrl:1
	v_fmac_f32_dpp v225, v99, v183 row_shr:1 row_mask:0xf bank_mask:0xf bound_ctrl:1
	v_fmac_f32_dpp v226, v100, v184 row_shr:1 row_mask:0xf bank_mask:0xf bound_ctrl:1
	v_fmac_f32_dpp v227, v101, v185 row_shr:1 row_mask:0xf bank_mask:0xf bound_ctrl:1
	v_fmac_f32_dpp v228, v74, v198 row_shr:1 row_mask:0xf bank_mask:0xf bound_ctrl:1
	v_fmac_f32_dpp v229, v75, v199 row_shr:1 row_mask:0xf bank_mask:0xf bound_ctrl:1
	v_fmac_f32_dpp v230, v76, v200 row_shr:1 row_mask:0xf bank_mask:0xf bound_ctrl:1
	v_fmac_f32_dpp v231, v77, v201 row_shr:1 row_mask:0xf bank_mask:0xf bound_ctrl:1
	v_fmac_f32_dpp v224, v98, v178 row_shr:2 row_mask:0xf bank_mask:0xf bound_ctrl:1
	v_fmac_f32_dpp v225, v99, v179 row_shr:2 row_mask:0xf bank_mask:0xf bound_ctrl:1
	v_fmac_f32_dpp v226, v100, v180 row_shr:2 row_mask:0xf bank_mask:0xf bound_ctrl:1
	v_fmac_f32_dpp v227, v101, v181 row_shr:2 row_mask:0xf bank_mask:0xf bound_ctrl:1
	v_fmac_f32_dpp v228, v74, v194 row_shr:2 row_mask:0xf bank_mask:0xf bound_ctrl:1
	v_fmac_f32_dpp v229, v75, v195 row_shr:2 row_mask:0xf bank_mask:0xf bound_ctrl:1
	v_fmac_f32_dpp v230, v76, v196 row_shr:2 row_mask:0xf bank_mask:0xf bound_ctrl:1
	v_fmac_f32_dpp v231, v77, v197 row_shr:2 row_mask:0xf bank_mask:0xf bound_ctrl:1
	v_fmac_f32_dpp v224, v114, v182 row_shl:15 row_mask:0xf bank_mask:0xf bound_ctrl:1
	v_fmac_f32_dpp v225, v115, v183 row_shl:15 row_mask:0xf bank_mask:0xf bound_ctrl:1
	v_fmac_f32_dpp v226, v116, v184 row_shl:15 row_mask:0xf bank_mask:0xf bound_ctrl:1
	v_fmac_f32_dpp v227, v117, v185 row_shl:15 row_mask:0xf bank_mask:0xf bound_ctrl:1
	v_fmac_f32_dpp v228, v86, v198 row_shl:15 row_mask:0xf bank_mask:0xf bound_ctrl:1
	v_fmac_f32_dpp v229, v87, v199 row_shl:15 row_mask:0xf bank_mask:0xf bound_ctrl:1
	v_fmac_f32_dpp v230, v88, v200 row_shl:15 row_mask:0xf bank_mask:0xf bound_ctrl:1
	v_fmac_f32_dpp v231, v89, v201 row_shl:15 row_mask:0xf bank_mask:0xf bound_ctrl:1
	v_fmac_f32_dpp v224, v114, v178 row_shl:14 row_mask:0xf bank_mask:0xf bound_ctrl:1
	v_fmac_f32_dpp v225, v115, v179 row_shl:14 row_mask:0xf bank_mask:0xf bound_ctrl:1
	v_fmac_f32_dpp v226, v116, v180 row_shl:14 row_mask:0xf bank_mask:0xf bound_ctrl:1
	v_fmac_f32_dpp v227, v117, v181 row_shl:14 row_mask:0xf bank_mask:0xf bound_ctrl:1
	v_fmac_f32_dpp v228, v86, v194 row_shl:14 row_mask:0xf bank_mask:0xf bound_ctrl:1
	v_fmac_f32_dpp v229, v87, v195 row_shl:14 row_mask:0xf bank_mask:0xf bound_ctrl:1
	v_fmac_f32_dpp v230, v88, v196 row_shl:14 row_mask:0xf bank_mask:0xf bound_ctrl:1
	v_fmac_f32_dpp v231, v89, v197 row_shl:14 row_mask:0xf bank_mask:0xf bound_ctrl:1
	v_pk_mul_f32 v[232:233], v[224:225], s[48:49] op_sel_hi:[1,0]
	v_pk_mul_f32 v[234:235], v[226:227], s[48:49] op_sel_hi:[1,0]
	v_exp_f32_e32 v232, v232
	v_exp_f32_e32 v233, v233
	v_exp_f32_e32 v234, v234
	v_exp_f32_e32 v235, v235
	v_pk_add_f32 v[232:233], v[232:233], 1.0 op_sel_hi:[1,0]
	v_pk_add_f32 v[234:235], v[234:235], 1.0 op_sel_hi:[1,0]
	v_rcp_f32_e32 v232, v232
	v_rcp_f32_e32 v233, v233
	v_rcp_f32_e32 v234, v234
	v_rcp_f32_e32 v235, v235
	v_lshl_add_u64 v[220:221], v[220:221], 0, s[96:97]
	v_pk_mul_f32 v[224:225], v[224:225], v[232:233]
	v_pk_mul_f32 v[226:227], v[226:227], v[234:235]
	v_pk_mul_f32 v[224:225], v[224:225], v[228:229]
	v_pk_mul_f32 v[226:227], v[226:227], v[230:231]
	v_cvt_pk_bf16_f32 v168, v224, v225
	v_cvt_pk_bf16_f32 v169, v226, v227
	global_store_dwordx2 v[220:221], v[168:169], off offset:32
	s_add_u32 s94, s26, s85
	s_addc_u32 s95, s27, 0
	v_lshl_add_u64 v[222:223], s[94:95], 0, v[216:217]
	v_lshl_add_u64 v[246:247], s[94:95], 0, v[218:219]
	s_and_saveexec_b64 s[46:47], s[6:7]
	global_store_dwordx4 v[222:223], v[82:85], off offset:64
	global_store_dwordx4 v[246:247], v[66:69], off offset:64
	s_or_b64 exec, exec, s[46:47]
	v_pk_fma_f32 v[224:225], v[82:83], v[186:187], v[190:191]
	v_pk_fma_f32 v[226:227], v[84:85], v[188:189], v[192:193]
	v_pk_fma_f32 v[228:229], v[66:67], v[202:203], v[206:207]
	v_pk_fma_f32 v[230:231], v[68:69], v[204:205], v[208:209]
	v_fmac_f32_dpp v224, v82, v182 row_shr:1 row_mask:0xf bank_mask:0xf bound_ctrl:1
	v_fmac_f32_dpp v225, v83, v183 row_shr:1 row_mask:0xf bank_mask:0xf bound_ctrl:1
	v_fmac_f32_dpp v226, v84, v184 row_shr:1 row_mask:0xf bank_mask:0xf bound_ctrl:1
	v_fmac_f32_dpp v227, v85, v185 row_shr:1 row_mask:0xf bank_mask:0xf bound_ctrl:1
	v_fmac_f32_dpp v228, v66, v198 row_shr:1 row_mask:0xf bank_mask:0xf bound_ctrl:1
	v_fmac_f32_dpp v229, v67, v199 row_shr:1 row_mask:0xf bank_mask:0xf bound_ctrl:1
	v_fmac_f32_dpp v230, v68, v200 row_shr:1 row_mask:0xf bank_mask:0xf bound_ctrl:1
	v_fmac_f32_dpp v231, v69, v201 row_shr:1 row_mask:0xf bank_mask:0xf bound_ctrl:1
	v_fmac_f32_dpp v224, v82, v178 row_shr:2 row_mask:0xf bank_mask:0xf bound_ctrl:1
	v_fmac_f32_dpp v225, v83, v179 row_shr:2 row_mask:0xf bank_mask:0xf bound_ctrl:1
	v_fmac_f32_dpp v226, v84, v180 row_shr:2 row_mask:0xf bank_mask:0xf bound_ctrl:1
	v_fmac_f32_dpp v227, v85, v181 row_shr:2 row_mask:0xf bank_mask:0xf bound_ctrl:1
	v_fmac_f32_dpp v228, v66, v194 row_shr:2 row_mask:0xf bank_mask:0xf bound_ctrl:1
	v_fmac_f32_dpp v229, v67, v195 row_shr:2 row_mask:0xf bank_mask:0xf bound_ctrl:1
	v_fmac_f32_dpp v230, v68, v196 row_shr:2 row_mask:0xf bank_mask:0xf bound_ctrl:1
	v_fmac_f32_dpp v231, v69, v197 row_shr:2 row_mask:0xf bank_mask:0xf bound_ctrl:1
	v_fmac_f32_dpp v224, v98, v182 row_shl:15 row_mask:0xf bank_mask:0xf bound_ctrl:1
	v_fmac_f32_dpp v225, v99, v183 row_shl:15 row_mask:0xf bank_mask:0xf bound_ctrl:1
	v_fmac_f32_dpp v226, v100, v184 row_shl:15 row_mask:0xf bank_mask:0xf bound_ctrl:1
	v_fmac_f32_dpp v227, v101, v185 row_shl:15 row_mask:0xf bank_mask:0xf bound_ctrl:1
	v_fmac_f32_dpp v228, v74, v198 row_shl:15 row_mask:0xf bank_mask:0xf bound_ctrl:1
	v_fmac_f32_dpp v229, v75, v199 row_shl:15 row_mask:0xf bank_mask:0xf bound_ctrl:1
	v_fmac_f32_dpp v230, v76, v200 row_shl:15 row_mask:0xf bank_mask:0xf bound_ctrl:1
	v_fmac_f32_dpp v231, v77, v201 row_shl:15 row_mask:0xf bank_mask:0xf bound_ctrl:1
	v_fmac_f32_dpp v224, v98, v178 row_shl:14 row_mask:0xf bank_mask:0xf bound_ctrl:1
	v_fmac_f32_dpp v225, v99, v179 row_shl:14 row_mask:0xf bank_mask:0xf bound_ctrl:1
	v_fmac_f32_dpp v226, v100, v180 row_shl:14 row_mask:0xf bank_mask:0xf bound_ctrl:1
	v_fmac_f32_dpp v227, v101, v181 row_shl:14 row_mask:0xf bank_mask:0xf bound_ctrl:1
	v_fmac_f32_dpp v228, v74, v194 row_shl:14 row_mask:0xf bank_mask:0xf bound_ctrl:1
	v_fmac_f32_dpp v229, v75, v195 row_shl:14 row_mask:0xf bank_mask:0xf bound_ctrl:1
	v_fmac_f32_dpp v230, v76, v196 row_shl:14 row_mask:0xf bank_mask:0xf bound_ctrl:1
	v_fmac_f32_dpp v231, v77, v197 row_shl:14 row_mask:0xf bank_mask:0xf bound_ctrl:1
	v_pk_mul_f32 v[232:233], v[224:225], s[48:49] op_sel_hi:[1,0]
	v_pk_mul_f32 v[234:235], v[226:227], s[48:49] op_sel_hi:[1,0]
	v_exp_f32_e32 v232, v232
	v_exp_f32_e32 v233, v233
	v_exp_f32_e32 v234, v234
	v_exp_f32_e32 v235, v235
	v_pk_add_f32 v[232:233], v[232:233], 1.0 op_sel_hi:[1,0]
	v_pk_add_f32 v[234:235], v[234:235], 1.0 op_sel_hi:[1,0]
	v_rcp_f32_e32 v232, v232
	v_rcp_f32_e32 v233, v233
	v_rcp_f32_e32 v234, v234
	v_rcp_f32_e32 v235, v235
	v_lshl_add_u64 v[220:221], v[220:221], 0, s[96:97]
	v_pk_mul_f32 v[224:225], v[224:225], v[232:233]
	v_pk_mul_f32 v[226:227], v[226:227], v[234:235]
	v_pk_mul_f32 v[224:225], v[224:225], v[228:229]
	v_pk_mul_f32 v[226:227], v[226:227], v[230:231]
	v_cvt_pk_bf16_f32 v168, v224, v225
	v_cvt_pk_bf16_f32 v169, v226, v227
	global_store_dwordx2 v[220:221], v[168:169], off offset:32
	s_add_i32 s84, s39, 2
	s_mul_i32 s85, s84, 0xb0000
	s_add_u32 s94, s22, s85
	s_addc_u32 s95, s23, 0
	v_lshl_add_u64 v[220:221], s[94:95], 0, v[210:211]
	s_mul_i32 s85, s84, 0x16000
	s_add_u32 s94, s24, s85
	s_addc_u32 s95, s25, 0
	v_lshl_add_u64 v[222:223], s[94:95], 0, v[212:213]
	v_lshl_add_u64 v[246:247], s[94:95], 0, v[214:215]
	s_and_saveexec_b64 s[46:47], s[4:5]
	global_store_dwordx4 v[222:223], v[58:61], off offset:64
	global_store_dwordx4 v[246:247], v[38:41], off offset:64
	s_or_b64 exec, exec, s[46:47]
	v_pk_fma_f32 v[224:225], v[58:59], v[186:187], v[190:191]
	v_pk_fma_f32 v[226:227], v[60:61], v[188:189], v[192:193]
	v_pk_fma_f32 v[228:229], v[38:39], v[202:203], v[206:207]
	v_pk_fma_f32 v[230:231], v[40:41], v[204:205], v[208:209]
	v_fmac_f32_dpp v224, v58, v182 row_shr:1 row_mask:0xf bank_mask:0xf bound_ctrl:1
	v_fmac_f32_dpp v225, v59, v183 row_shr:1 row_mask:0xf bank_mask:0xf bound_ctrl:1
	v_fmac_f32_dpp v226, v60, v184 row_shr:1 row_mask:0xf bank_mask:0xf bound_ctrl:1
	v_fmac_f32_dpp v227, v61, v185 row_shr:1 row_mask:0xf bank_mask:0xf bound_ctrl:1
	v_fmac_f32_dpp v228, v38, v198 row_shr:1 row_mask:0xf bank_mask:0xf bound_ctrl:1
	v_fmac_f32_dpp v229, v39, v199 row_shr:1 row_mask:0xf bank_mask:0xf bound_ctrl:1
	v_fmac_f32_dpp v230, v40, v200 row_shr:1 row_mask:0xf bank_mask:0xf bound_ctrl:1
	v_fmac_f32_dpp v231, v41, v201 row_shr:1 row_mask:0xf bank_mask:0xf bound_ctrl:1
	v_fmac_f32_dpp v224, v58, v178 row_shr:2 row_mask:0xf bank_mask:0xf bound_ctrl:1
	v_fmac_f32_dpp v225, v59, v179 row_shr:2 row_mask:0xf bank_mask:0xf bound_ctrl:1
	v_fmac_f32_dpp v226, v60, v180 row_shr:2 row_mask:0xf bank_mask:0xf bound_ctrl:1
	v_fmac_f32_dpp v227, v61, v181 row_shr:2 row_mask:0xf bank_mask:0xf bound_ctrl:1
	v_fmac_f32_dpp v228, v38, v194 row_shr:2 row_mask:0xf bank_mask:0xf bound_ctrl:1
	v_fmac_f32_dpp v229, v39, v195 row_shr:2 row_mask:0xf bank_mask:0xf bound_ctrl:1
	v_fmac_f32_dpp v230, v40, v196 row_shr:2 row_mask:0xf bank_mask:0xf bound_ctrl:1
	v_fmac_f32_dpp v231, v41, v197 row_shr:2 row_mask:0xf bank_mask:0xf bound_ctrl:1
	v_pk_mul_f32 v[232:233], v[224:225], s[48:49] op_sel_hi:[1,0]
	v_pk_mul_f32 v[234:235], v[226:227], s[48:49] op_sel_hi:[1,0]
	v_exp_f32_e32 v232, v232
	v_exp_f32_e32 v233, v233
	v_exp_f32_e32 v234, v234
	v_exp_f32_e32 v235, v235
	v_pk_add_f32 v[232:233], v[232:233], 1.0 op_sel_hi:[1,0]
	v_pk_add_f32 v[234:235], v[234:235], 1.0 op_sel_hi:[1,0]
	v_rcp_f32_e32 v232, v232
	v_rcp_f32_e32 v233, v233
	v_rcp_f32_e32 v234, v234
	v_rcp_f32_e32 v235, v235
	v_pk_mul_f32 v[224:225], v[224:225], v[232:233]
	v_pk_mul_f32 v[226:227], v[226:227], v[234:235]
	v_pk_mul_f32 v[224:225], v[224:225], v[228:229]
	v_pk_mul_f32 v[226:227], v[226:227], v[230:231]
	v_cvt_pk_bf16_f32 v168, v224, v225
	v_cvt_pk_bf16_f32 v169, v226, v227
	s_and_saveexec_b64 s[46:47], s[8:9]
	global_store_dwordx2 v[220:221], v[168:169], off offset:32
	s_or_b64 exec, exec, s[46:47]
	v_pk_fma_f32 v[224:225], v[50:51], v[186:187], v[190:191]
	v_pk_fma_f32 v[226:227], v[52:53], v[188:189], v[192:193]
	v_pk_fma_f32 v[228:229], v[22:23], v[202:203], v[206:207]
	v_pk_fma_f32 v[230:231], v[24:25], v[204:205], v[208:209]
	v_fmac_f32_dpp v224, v50, v182 row_shr:1 row_mask:0xf bank_mask:0xf bound_ctrl:1
	v_fmac_f32_dpp v225, v51, v183 row_shr:1 row_mask:0xf bank_mask:0xf bound_ctrl:1
	v_fmac_f32_dpp v226, v52, v184 row_shr:1 row_mask:0xf bank_mask:0xf bound_ctrl:1
	v_fmac_f32_dpp v227, v53, v185 row_shr:1 row_mask:0xf bank_mask:0xf bound_ctrl:1
	v_fmac_f32_dpp v228, v22, v198 row_shr:1 row_mask:0xf bank_mask:0xf bound_ctrl:1
	v_fmac_f32_dpp v229, v23, v199 row_shr:1 row_mask:0xf bank_mask:0xf bound_ctrl:1
	v_fmac_f32_dpp v230, v24, v200 row_shr:1 row_mask:0xf bank_mask:0xf bound_ctrl:1
	v_fmac_f32_dpp v231, v25, v201 row_shr:1 row_mask:0xf bank_mask:0xf bound_ctrl:1
	v_fmac_f32_dpp v224, v50, v178 row_shr:2 row_mask:0xf bank_mask:0xf bound_ctrl:1
	v_fmac_f32_dpp v225, v51, v179 row_shr:2 row_mask:0xf bank_mask:0xf bound_ctrl:1
	v_fmac_f32_dpp v226, v52, v180 row_shr:2 row_mask:0xf bank_mask:0xf bound_ctrl:1
	v_fmac_f32_dpp v227, v53, v181 row_shr:2 row_mask:0xf bank_mask:0xf bound_ctrl:1
	v_fmac_f32_dpp v228, v22, v194 row_shr:2 row_mask:0xf bank_mask:0xf bound_ctrl:1
	v_fmac_f32_dpp v229, v23, v195 row_shr:2 row_mask:0xf bank_mask:0xf bound_ctrl:1
	v_fmac_f32_dpp v230, v24, v196 row_shr:2 row_mask:0xf bank_mask:0xf bound_ctrl:1
	v_fmac_f32_dpp v231, v25, v197 row_shr:2 row_mask:0xf bank_mask:0xf bound_ctrl:1
	v_fmac_f32_dpp v224, v58, v182 row_shl:15 row_mask:0xf bank_mask:0xf bound_ctrl:1
	v_fmac_f32_dpp v225, v59, v183 row_shl:15 row_mask:0xf bank_mask:0xf bound_ctrl:1
	v_fmac_f32_dpp v226, v60, v184 row_shl:15 row_mask:0xf bank_mask:0xf bound_ctrl:1
	v_fmac_f32_dpp v227, v61, v185 row_shl:15 row_mask:0xf bank_mask:0xf bound_ctrl:1
	v_fmac_f32_dpp v228, v38, v198 row_shl:15 row_mask:0xf bank_mask:0xf bound_ctrl:1
	v_fmac_f32_dpp v229, v39, v199 row_shl:15 row_mask:0xf bank_mask:0xf bound_ctrl:1
	v_fmac_f32_dpp v230, v40, v200 row_shl:15 row_mask:0xf bank_mask:0xf bound_ctrl:1
	v_fmac_f32_dpp v231, v41, v201 row_shl:15 row_mask:0xf bank_mask:0xf bound_ctrl:1
	v_fmac_f32_dpp v224, v58, v178 row_shl:14 row_mask:0xf bank_mask:0xf bound_ctrl:1
	v_fmac_f32_dpp v225, v59, v179 row_shl:14 row_mask:0xf bank_mask:0xf bound_ctrl:1
	v_fmac_f32_dpp v226, v60, v180 row_shl:14 row_mask:0xf bank_mask:0xf bound_ctrl:1
	v_fmac_f32_dpp v227, v61, v181 row_shl:14 row_mask:0xf bank_mask:0xf bound_ctrl:1
	v_fmac_f32_dpp v228, v38, v194 row_shl:14 row_mask:0xf bank_mask:0xf bound_ctrl:1
	v_fmac_f32_dpp v229, v39, v195 row_shl:14 row_mask:0xf bank_mask:0xf bound_ctrl:1
	v_fmac_f32_dpp v230, v40, v196 row_shl:14 row_mask:0xf bank_mask:0xf bound_ctrl:1
	v_fmac_f32_dpp v231, v41, v197 row_shl:14 row_mask:0xf bank_mask:0xf bound_ctrl:1
	v_pk_mul_f32 v[232:233], v[224:225], s[48:49] op_sel_hi:[1,0]
	v_pk_mul_f32 v[234:235], v[226:227], s[48:49] op_sel_hi:[1,0]
	v_exp_f32_e32 v232, v232
	v_exp_f32_e32 v233, v233
	v_exp_f32_e32 v234, v234
	v_exp_f32_e32 v235, v235
	v_pk_add_f32 v[232:233], v[232:233], 1.0 op_sel_hi:[1,0]
	v_pk_add_f32 v[234:235], v[234:235], 1.0 op_sel_hi:[1,0]
	v_rcp_f32_e32 v232, v232
	v_rcp_f32_e32 v233, v233
	v_rcp_f32_e32 v234, v234
	v_rcp_f32_e32 v235, v235
	v_lshl_add_u64 v[220:221], v[220:221], 0, s[96:97]
	v_pk_mul_f32 v[224:225], v[224:225], v[232:233]
	v_pk_mul_f32 v[226:227], v[226:227], v[234:235]
	v_pk_mul_f32 v[224:225], v[224:225], v[228:229]
	v_pk_mul_f32 v[226:227], v[226:227], v[230:231]
	v_cvt_pk_bf16_f32 v168, v224, v225
	v_cvt_pk_bf16_f32 v169, v226, v227
	global_store_dwordx2 v[220:221], v[168:169], off offset:32
	v_pk_fma_f32 v[224:225], v[34:35], v[186:187], v[190:191]
	v_pk_fma_f32 v[226:227], v[36:37], v[188:189], v[192:193]
	v_pk_fma_f32 v[228:229], v[10:11], v[202:203], v[206:207]
	v_pk_fma_f32 v[230:231], v[12:13], v[204:205], v[208:209]
	v_fmac_f32_dpp v224, v34, v182 row_shr:1 row_mask:0xf bank_mask:0xf bound_ctrl:1
	v_fmac_f32_dpp v225, v35, v183 row_shr:1 row_mask:0xf bank_mask:0xf bound_ctrl:1
	v_fmac_f32_dpp v226, v36, v184 row_shr:1 row_mask:0xf bank_mask:0xf bound_ctrl:1
	v_fmac_f32_dpp v227, v37, v185 row_shr:1 row_mask:0xf bank_mask:0xf bound_ctrl:1
	v_fmac_f32_dpp v228, v10, v198 row_shr:1 row_mask:0xf bank_mask:0xf bound_ctrl:1
	v_fmac_f32_dpp v229, v11, v199 row_shr:1 row_mask:0xf bank_mask:0xf bound_ctrl:1
	v_fmac_f32_dpp v230, v12, v200 row_shr:1 row_mask:0xf bank_mask:0xf bound_ctrl:1
	v_fmac_f32_dpp v231, v13, v201 row_shr:1 row_mask:0xf bank_mask:0xf bound_ctrl:1
	v_fmac_f32_dpp v224, v34, v178 row_shr:2 row_mask:0xf bank_mask:0xf bound_ctrl:1
	v_fmac_f32_dpp v225, v35, v179 row_shr:2 row_mask:0xf bank_mask:0xf bound_ctrl:1
	v_fmac_f32_dpp v226, v36, v180 row_shr:2 row_mask:0xf bank_mask:0xf bound_ctrl:1
	v_fmac_f32_dpp v227, v37, v181 row_shr:2 row_mask:0xf bank_mask:0xf bound_ctrl:1
	v_fmac_f32_dpp v228, v10, v194 row_shr:2 row_mask:0xf bank_mask:0xf bound_ctrl:1
	v_fmac_f32_dpp v229, v11, v195 row_shr:2 row_mask:0xf bank_mask:0xf bound_ctrl:1
	v_fmac_f32_dpp v230, v12, v196 row_shr:2 row_mask:0xf bank_mask:0xf bound_ctrl:1
	v_fmac_f32_dpp v231, v13, v197 row_shr:2 row_mask:0xf bank_mask:0xf bound_ctrl:1
	v_fmac_f32_dpp v224, v50, v182 row_shl:15 row_mask:0xf bank_mask:0xf bound_ctrl:1
	v_fmac_f32_dpp v225, v51, v183 row_shl:15 row_mask:0xf bank_mask:0xf bound_ctrl:1
	v_fmac_f32_dpp v226, v52, v184 row_shl:15 row_mask:0xf bank_mask:0xf bound_ctrl:1
	v_fmac_f32_dpp v227, v53, v185 row_shl:15 row_mask:0xf bank_mask:0xf bound_ctrl:1
	v_fmac_f32_dpp v228, v22, v198 row_shl:15 row_mask:0xf bank_mask:0xf bound_ctrl:1
	v_fmac_f32_dpp v229, v23, v199 row_shl:15 row_mask:0xf bank_mask:0xf bound_ctrl:1
	v_fmac_f32_dpp v230, v24, v200 row_shl:15 row_mask:0xf bank_mask:0xf bound_ctrl:1
	v_fmac_f32_dpp v231, v25, v201 row_shl:15 row_mask:0xf bank_mask:0xf bound_ctrl:1
	v_fmac_f32_dpp v224, v50, v178 row_shl:14 row_mask:0xf bank_mask:0xf bound_ctrl:1
	v_fmac_f32_dpp v225, v51, v179 row_shl:14 row_mask:0xf bank_mask:0xf bound_ctrl:1
	v_fmac_f32_dpp v226, v52, v180 row_shl:14 row_mask:0xf bank_mask:0xf bound_ctrl:1
	v_fmac_f32_dpp v227, v53, v181 row_shl:14 row_mask:0xf bank_mask:0xf bound_ctrl:1
	v_fmac_f32_dpp v228, v22, v194 row_shl:14 row_mask:0xf bank_mask:0xf bound_ctrl:1
	v_fmac_f32_dpp v229, v23, v195 row_shl:14 row_mask:0xf bank_mask:0xf bound_ctrl:1
	v_fmac_f32_dpp v230, v24, v196 row_shl:14 row_mask:0xf bank_mask:0xf bound_ctrl:1
	v_fmac_f32_dpp v231, v25, v197 row_shl:14 row_mask:0xf bank_mask:0xf bound_ctrl:1
	v_pk_mul_f32 v[232:233], v[224:225], s[48:49] op_sel_hi:[1,0]
	v_pk_mul_f32 v[234:235], v[226:227], s[48:49] op_sel_hi:[1,0]
	v_exp_f32_e32 v232, v232
	v_exp_f32_e32 v233, v233
	v_exp_f32_e32 v234, v234
	v_exp_f32_e32 v235, v235
	v_pk_add_f32 v[232:233], v[232:233], 1.0 op_sel_hi:[1,0]
	v_pk_add_f32 v[234:235], v[234:235], 1.0 op_sel_hi:[1,0]
	v_rcp_f32_e32 v232, v232
	v_rcp_f32_e32 v233, v233
	v_rcp_f32_e32 v234, v234
	v_rcp_f32_e32 v235, v235
	v_lshl_add_u64 v[220:221], v[220:221], 0, s[96:97]
	v_pk_mul_f32 v[224:225], v[224:225], v[232:233]
	v_pk_mul_f32 v[226:227], v[226:227], v[234:235]
	v_pk_mul_f32 v[224:225], v[224:225], v[228:229]
	v_pk_mul_f32 v[226:227], v[226:227], v[230:231]
	v_cvt_pk_bf16_f32 v168, v224, v225
	v_cvt_pk_bf16_f32 v169, v226, v227
	global_store_dwordx2 v[220:221], v[168:169], off offset:32
	s_add_u32 s94, s26, s85
	s_addc_u32 s95, s27, 0
	v_lshl_add_u64 v[222:223], s[94:95], 0, v[216:217]
	v_lshl_add_u64 v[246:247], s[94:95], 0, v[218:219]
	s_and_saveexec_b64 s[46:47], s[6:7]
	global_store_dwordx4 v[222:223], v[18:21], off offset:64
	global_store_dwordx4 v[246:247], v[2:5], off offset:64
	s_or_b64 exec, exec, s[46:47]
	v_pk_fma_f32 v[224:225], v[18:19], v[186:187], v[190:191]
	v_pk_fma_f32 v[226:227], v[20:21], v[188:189], v[192:193]
	v_pk_fma_f32 v[228:229], v[2:3], v[202:203], v[206:207]
	v_pk_fma_f32 v[230:231], v[4:5], v[204:205], v[208:209]
	v_fmac_f32_dpp v224, v18, v182 row_shr:1 row_mask:0xf bank_mask:0xf bound_ctrl:1
	v_fmac_f32_dpp v225, v19, v183 row_shr:1 row_mask:0xf bank_mask:0xf bound_ctrl:1
	v_fmac_f32_dpp v226, v20, v184 row_shr:1 row_mask:0xf bank_mask:0xf bound_ctrl:1
	v_fmac_f32_dpp v227, v21, v185 row_shr:1 row_mask:0xf bank_mask:0xf bound_ctrl:1
	v_fmac_f32_dpp v228, v2, v198 row_shr:1 row_mask:0xf bank_mask:0xf bound_ctrl:1
	v_fmac_f32_dpp v229, v3, v199 row_shr:1 row_mask:0xf bank_mask:0xf bound_ctrl:1
	v_fmac_f32_dpp v230, v4, v200 row_shr:1 row_mask:0xf bank_mask:0xf bound_ctrl:1
	v_fmac_f32_dpp v231, v5, v201 row_shr:1 row_mask:0xf bank_mask:0xf bound_ctrl:1
	v_fmac_f32_dpp v224, v18, v178 row_shr:2 row_mask:0xf bank_mask:0xf bound_ctrl:1
	v_fmac_f32_dpp v225, v19, v179 row_shr:2 row_mask:0xf bank_mask:0xf bound_ctrl:1
	v_fmac_f32_dpp v226, v20, v180 row_shr:2 row_mask:0xf bank_mask:0xf bound_ctrl:1
	v_fmac_f32_dpp v227, v21, v181 row_shr:2 row_mask:0xf bank_mask:0xf bound_ctrl:1
	v_fmac_f32_dpp v228, v2, v194 row_shr:2 row_mask:0xf bank_mask:0xf bound_ctrl:1
	v_fmac_f32_dpp v229, v3, v195 row_shr:2 row_mask:0xf bank_mask:0xf bound_ctrl:1
	v_fmac_f32_dpp v230, v4, v196 row_shr:2 row_mask:0xf bank_mask:0xf bound_ctrl:1
	v_fmac_f32_dpp v231, v5, v197 row_shr:2 row_mask:0xf bank_mask:0xf bound_ctrl:1
	v_fmac_f32_dpp v224, v34, v182 row_shl:15 row_mask:0xf bank_mask:0xf bound_ctrl:1
	v_fmac_f32_dpp v225, v35, v183 row_shl:15 row_mask:0xf bank_mask:0xf bound_ctrl:1
	v_fmac_f32_dpp v226, v36, v184 row_shl:15 row_mask:0xf bank_mask:0xf bound_ctrl:1
	v_fmac_f32_dpp v227, v37, v185 row_shl:15 row_mask:0xf bank_mask:0xf bound_ctrl:1
	v_fmac_f32_dpp v228, v10, v198 row_shl:15 row_mask:0xf bank_mask:0xf bound_ctrl:1
	v_fmac_f32_dpp v229, v11, v199 row_shl:15 row_mask:0xf bank_mask:0xf bound_ctrl:1
	v_fmac_f32_dpp v230, v12, v200 row_shl:15 row_mask:0xf bank_mask:0xf bound_ctrl:1
	v_fmac_f32_dpp v231, v13, v201 row_shl:15 row_mask:0xf bank_mask:0xf bound_ctrl:1
	v_fmac_f32_dpp v224, v34, v178 row_shl:14 row_mask:0xf bank_mask:0xf bound_ctrl:1
	v_fmac_f32_dpp v225, v35, v179 row_shl:14 row_mask:0xf bank_mask:0xf bound_ctrl:1
	v_fmac_f32_dpp v226, v36, v180 row_shl:14 row_mask:0xf bank_mask:0xf bound_ctrl:1
	v_fmac_f32_dpp v227, v37, v181 row_shl:14 row_mask:0xf bank_mask:0xf bound_ctrl:1
	v_fmac_f32_dpp v228, v10, v194 row_shl:14 row_mask:0xf bank_mask:0xf bound_ctrl:1
	v_fmac_f32_dpp v229, v11, v195 row_shl:14 row_mask:0xf bank_mask:0xf bound_ctrl:1
	v_fmac_f32_dpp v230, v12, v196 row_shl:14 row_mask:0xf bank_mask:0xf bound_ctrl:1
	v_fmac_f32_dpp v231, v13, v197 row_shl:14 row_mask:0xf bank_mask:0xf bound_ctrl:1
	v_pk_mul_f32 v[232:233], v[224:225], s[48:49] op_sel_hi:[1,0]
	v_pk_mul_f32 v[234:235], v[226:227], s[48:49] op_sel_hi:[1,0]
	v_exp_f32_e32 v232, v232
	v_exp_f32_e32 v233, v233
	v_exp_f32_e32 v234, v234
	v_exp_f32_e32 v235, v235
	v_pk_add_f32 v[232:233], v[232:233], 1.0 op_sel_hi:[1,0]
	v_pk_add_f32 v[234:235], v[234:235], 1.0 op_sel_hi:[1,0]
	v_rcp_f32_e32 v232, v232
	v_rcp_f32_e32 v233, v233
	v_rcp_f32_e32 v234, v234
	v_rcp_f32_e32 v235, v235
	v_lshl_add_u64 v[220:221], v[220:221], 0, s[96:97]
	v_pk_mul_f32 v[224:225], v[224:225], v[232:233]
	v_pk_mul_f32 v[226:227], v[226:227], v[234:235]
	v_pk_mul_f32 v[224:225], v[224:225], v[228:229]
	v_pk_mul_f32 v[226:227], v[226:227], v[230:231]
	v_cvt_pk_bf16_f32 v168, v224, v225
	v_cvt_pk_bf16_f32 v169, v226, v227
	global_store_dwordx2 v[220:221], v[168:169], off offset:32
	s_branch .LBB0_1094
